# stack + phase E cross-q wave sums and phase C row-norm butterfly via DPP/permlane swaps (serialized ds_bpermute chains removed)
# baseline (speedup 1.0000x reference)
.LBB0_574:
	s_add_u32 s33, s56, s46
	s_addc_u32 s40, s57, s47
	s_lshl_b64 s[38:39], s[38:39], 11
	s_add_u32 s38, s33, s38
	s_addc_u32 s39, s40, s39
	s_lshl_b64 s[40:41], s[26:27], 11
	s_add_u32 s33, s56, s50
	v_lshl_add_u64 v[6:7], v[90:91], 0, s[40:41]
	s_addc_u32 s46, s57, s51
	s_lshl_b64 s[40:41], s[48:49], 8
	s_add_u32 s40, s33, s40
	s_addc_u32 s41, s46, s41
	global_load_dwordx4 v[16:19], v[6:7], off
	global_load_dwordx4 v[8:11], v[6:7], off offset:1024
	global_load_dwordx4 v[12:15], v4, s[38:39]
	s_nop 0
	global_load_dwordx4 v[4:7], v4, s[38:39] offset:1024
	s_nop 0
	global_load_dword v119, v104, s[40:41]
	s_waitcnt vmcnt(0)
	v_mov_b32_e32 v126, v81
	v_mov_b32_e32 v127, v73
	v_mov_b32_e32 v124, v80
	v_mov_b32_e32 v125, v72
	v_pk_mul_f32 v[126:127], v[126:127], v[126:127]
	v_mov_b32_e32 v128, v83
	v_mov_b32_e32 v129, v75
	v_pk_fma_f32 v[124:125], v[124:125], v[124:125], v[126:127]
	v_mov_b32_e32 v126, v82
	v_mov_b32_e32 v127, v74
	v_pk_mul_f32 v[128:129], v[128:129], v[128:129]
	v_mul_f32_e32 v131, v51, v51
	v_pk_fma_f32 v[126:127], v[126:127], v[126:127], v[128:129]
	v_mov_b32_e32 v128, v79
	v_pk_add_f32 v[124:125], v[124:125], v[126:127]
	v_mov_b32_e32 v126, v77
	v_mov_b32_e32 v127, v69
	v_add_f32_e32 v130, v124, v125
	v_mov_b32_e32 v124, v76
	v_mov_b32_e32 v125, v68
	v_pk_mul_f32 v[126:127], v[126:127], v[126:127]
	v_mov_b32_e32 v129, v71
	v_pk_fma_f32 v[124:125], v[124:125], v[124:125], v[126:127]
	v_mov_b32_e32 v126, v78
	v_mov_b32_e32 v127, v70
	v_pk_mul_f32 v[128:129], v[128:129], v[128:129]
	v_fmac_f32_e32 v131, v50, v50
	v_pk_fma_f32 v[126:127], v[126:127], v[126:127], v[128:129]
	v_mul_f32_e32 v128, v63, v63
	v_pk_add_f32 v[124:125], v[124:125], v[126:127]
	v_mul_f32_e32 v126, v65, v65
	v_mul_f32_e32 v127, v67, v67
	v_fmac_f32_e32 v126, v64, v64
	v_fmac_f32_e32 v127, v66, v66
	v_add_f32_e32 v126, v126, v127
	v_mul_f32_e32 v127, v61, v61
	v_fmac_f32_e32 v127, v60, v60
	v_fmac_f32_e32 v128, v62, v62
	v_add_f32_e32 v127, v127, v128
	v_mul_f32_e32 v128, v57, v57
	v_mul_f32_e32 v129, v59, v59
	v_fmac_f32_e32 v128, v56, v56
	v_fmac_f32_e32 v129, v58, v58
	v_add_f32_e32 v128, v128, v129
	v_add_f32_e32 v126, v126, v128
	v_mul_f32_e32 v128, v53, v53
	v_mul_f32_e32 v129, v55, v55
	v_fmac_f32_e32 v128, v52, v52
	v_fmac_f32_e32 v129, v54, v54
	v_add_f32_e32 v128, v128, v129
	v_mul_f32_e32 v129, v49, v49
	v_fmac_f32_e32 v129, v48, v48
	v_add_f32_e32 v129, v129, v131
	v_mul_f32_e32 v131, v45, v45
	v_mul_f32_e32 v132, v47, v47
	v_fmac_f32_e32 v131, v44, v44
	v_fmac_f32_e32 v132, v46, v46
	v_add_f32_e32 v131, v131, v132
	v_mul_f32_e32 v132, v41, v41
	v_mul_f32_e32 v133, v43, v43
	v_fmac_f32_e32 v132, v40, v40
	v_fmac_f32_e32 v133, v42, v42
	v_add_f32_e32 v132, v132, v133
	v_add_f32_e32 v129, v129, v132
	v_mul_f32_e32 v132, v37, v37
	v_mul_f32_e32 v133, v39, v39
	v_fmac_f32_e32 v132, v36, v36
	v_fmac_f32_e32 v133, v38, v38
	v_add_f32_e32 v132, v132, v133
	v_mul_f32_e32 v133, v33, v33
	v_mul_f32_e32 v134, v35, v35
	v_fmac_f32_e32 v133, v32, v32
	v_fmac_f32_e32 v134, v34, v34
	v_add_f32_e32 v133, v133, v134
	v_mul_f32_e32 v134, v29, v29
	v_mul_f32_e32 v135, v31, v31
	v_fmac_f32_e32 v134, v28, v28
	v_fmac_f32_e32 v135, v30, v30
	v_add_f32_e32 v134, v134, v135
	v_mul_f32_e32 v135, v25, v25
	v_mul_f32_e32 v136, v27, v27
	v_fmac_f32_e32 v135, v24, v24
	v_fmac_f32_e32 v136, v26, v26
	v_add_f32_e32 v135, v135, v136
	v_add_f32_e32 v133, v133, v135
	v_mul_f32_e32 v135, v21, v21
	v_mul_f32_e32 v136, v23, v23
	v_fmac_f32_e32 v135, v20, v20
	v_fmac_f32_e32 v136, v22, v22
	v_add_f32_e32 v135, v135, v136
	v_mul_f32_e32 v136, v17, v17
	v_mul_f32_e32 v137, v19, v19
	v_fmac_f32_e32 v136, v16, v16
	v_fmac_f32_e32 v137, v18, v18
	v_add_f32_e32 v136, v136, v137
	v_mul_f32_e32 v137, v13, v13
	v_mul_f32_e32 v138, v15, v15
	v_fmac_f32_e32 v137, v12, v12
	v_fmac_f32_e32 v138, v14, v14
	v_add_f32_e32 v137, v137, v138
	v_mul_f32_e32 v138, v9, v9
	v_mul_f32_e32 v139, v11, v11
	v_fmac_f32_e32 v138, v8, v8
	v_fmac_f32_e32 v139, v10, v10
	v_add_f32_e32 v138, v138, v139
	v_add_f32_e32 v136, v136, v138
	v_mul_f32_e32 v138, v5, v5
	v_mul_f32_e32 v139, v7, v7
	v_fmac_f32_e32 v138, v4, v4
	v_fmac_f32_e32 v139, v6, v6
	v_add_f32_e32 v138, v138, v139
	ds_bpermute_b32 v139, v87, v130
	v_add_f32_e32 v124, v124, v125
	v_add_f32_e32 v127, v127, v128
	v_add_f32_e32 v131, v131, v132
	v_add_f32_e32 v134, v134, v135
	s_waitcnt lgkmcnt(0)
	v_add_f32_e32 v130, v130, v139
	ds_bpermute_b32 v139, v87, v124
	v_add_f32_e32 v137, v137, v138
	v_mul_f32_e32 v125, v123, v123
	ds_bpermute_b32 v125, v87, v125
	v_mul_f32_e32 v128, v122, v122
	s_waitcnt lgkmcnt(1)
	v_add_f32_e32 v124, v124, v139
	ds_bpermute_b32 v139, v87, v126
	ds_bpermute_b32 v128, v87, v128
	s_waitcnt lgkmcnt(2)
	v_fmac_f32_e32 v125, v123, v123
	v_mul_f32_e32 v132, v121, v121
	ds_bpermute_b32 v132, v87, v132
	s_waitcnt lgkmcnt(2)
	v_add_f32_e32 v126, v126, v139
	ds_bpermute_b32 v139, v87, v127
	s_waitcnt lgkmcnt(2)
	v_fmac_f32_e32 v128, v122, v122
	v_mul_f32_e32 v135, v120, v120
	s_waitcnt lgkmcnt(1)
	v_fmac_f32_e32 v132, v121, v121
	ds_bpermute_b32 v135, v87, v135
	s_waitcnt lgkmcnt(1)
	v_add_f32_e32 v127, v127, v139
	ds_bpermute_b32 v139, v87, v129
	v_mul_f32_e32 v138, v119, v119
	ds_bpermute_b32 v138, v87, v138
	s_waitcnt lgkmcnt(2)
	v_fmac_f32_e32 v135, v120, v120
	s_and_b32 s33, s26, 63
	s_waitcnt lgkmcnt(1)
	v_add_f32_e32 v129, v129, v139
	ds_bpermute_b32 v139, v87, v131
	s_waitcnt lgkmcnt(1)
	v_fmac_f32_e32 v138, v119, v119
	s_bitset1_b32 s33, 12
	s_and_b64 s[36:37], exec, s[36:37]
	s_cselect_b32 s36, s26, s33
	s_waitcnt lgkmcnt(0)
	v_add_f32_e32 v131, v131, v139
	ds_bpermute_b32 v139, v87, v133
	s_ashr_i32 s37, s36, 31
	s_lshl_b64 s[36:37], s[36:37], 8
	v_lshl_add_u64 v[104:105], v[88:89], 0, s[36:37]
	global_load_dwordx2 v[104:105], v[104:105], off
	s_waitcnt lgkmcnt(0)
	v_add_f32_e32 v133, v133, v139
	s_nop 1
	v_add_f32_dpp v134, v134, v134 quad_perm:[1,0,3,2] row_mask:0xf bank_mask:0xf
	s_mov_b32 s33, 0x56580000
	s_waitcnt lgkmcnt(0)
	s_nop 0
	s_nop 1
	v_add_f32_dpp v136, v136, v136 quad_perm:[1,0,3,2] row_mask:0xf bank_mask:0xf
	s_waitcnt lgkmcnt(0)
	s_nop 0
	s_nop 1
	v_add_f32_dpp v137, v137, v137 quad_perm:[1,0,3,2] row_mask:0xf bank_mask:0xf
	s_waitcnt lgkmcnt(0)
	s_nop 0
	s_nop 1
	v_add_f32_dpp v130, v130, v130 quad_perm:[2,3,0,1] row_mask:0xf bank_mask:0xf
	s_waitcnt lgkmcnt(0)
	s_nop 0
	s_nop 1
	v_add_f32_dpp v124, v124, v124 quad_perm:[2,3,0,1] row_mask:0xf bank_mask:0xf
	s_waitcnt lgkmcnt(0)
	s_nop 0
	s_nop 1
	v_add_f32_dpp v125, v125, v125 quad_perm:[2,3,0,1] row_mask:0xf bank_mask:0xf
	s_waitcnt lgkmcnt(0)
	s_nop 0
	s_nop 1
	v_add_f32_dpp v126, v126, v126 quad_perm:[2,3,0,1] row_mask:0xf bank_mask:0xf
	s_waitcnt lgkmcnt(0)
	s_nop 0
	s_nop 1
	v_add_f32_dpp v127, v127, v127 quad_perm:[2,3,0,1] row_mask:0xf bank_mask:0xf
	s_waitcnt lgkmcnt(0)
	s_nop 0
	s_nop 1
	v_add_f32_dpp v128, v128, v128 quad_perm:[2,3,0,1] row_mask:0xf bank_mask:0xf
	s_waitcnt lgkmcnt(0)
	s_nop 0
	s_nop 1
	v_add_f32_dpp v129, v129, v129 quad_perm:[2,3,0,1] row_mask:0xf bank_mask:0xf
	s_waitcnt lgkmcnt(0)
	s_nop 0
	s_nop 1
	v_add_f32_dpp v131, v131, v131 quad_perm:[2,3,0,1] row_mask:0xf bank_mask:0xf
	s_waitcnt lgkmcnt(0)
	s_nop 0
	s_nop 1
	v_add_f32_dpp v132, v132, v132 quad_perm:[2,3,0,1] row_mask:0xf bank_mask:0xf
	s_waitcnt lgkmcnt(0)
	s_nop 0
	s_nop 1
	v_add_f32_dpp v133, v133, v133 quad_perm:[2,3,0,1] row_mask:0xf bank_mask:0xf
	s_waitcnt lgkmcnt(0)
	s_nop 0
	s_nop 1
	v_add_f32_dpp v134, v134, v134 quad_perm:[2,3,0,1] row_mask:0xf bank_mask:0xf
	s_waitcnt lgkmcnt(0)
	s_nop 0
	s_nop 1
	v_add_f32_dpp v135, v135, v135 quad_perm:[2,3,0,1] row_mask:0xf bank_mask:0xf
	s_waitcnt lgkmcnt(0)
	s_nop 0
	s_nop 1
	v_add_f32_dpp v136, v136, v136 quad_perm:[2,3,0,1] row_mask:0xf bank_mask:0xf
	s_waitcnt lgkmcnt(0)
	s_nop 0
	s_nop 1
	v_add_f32_dpp v137, v137, v137 quad_perm:[2,3,0,1] row_mask:0xf bank_mask:0xf
	s_waitcnt lgkmcnt(0)
	s_nop 0
	s_nop 1
	v_add_f32_dpp v138, v138, v138 quad_perm:[2,3,0,1] row_mask:0xf bank_mask:0xf
	s_waitcnt lgkmcnt(0)
	s_nop 0
	s_nop 1
	v_add_f32_dpp v130, v130, v130 row_half_mirror row_mask:0xf bank_mask:0xf
	s_waitcnt lgkmcnt(0)
	s_nop 0
	s_nop 1
	v_add_f32_dpp v124, v124, v124 row_half_mirror row_mask:0xf bank_mask:0xf
	s_waitcnt lgkmcnt(0)
	s_nop 0
	s_nop 1
	v_add_f32_dpp v125, v125, v125 row_half_mirror row_mask:0xf bank_mask:0xf
	s_waitcnt lgkmcnt(0)
	s_nop 0
	s_nop 1
	v_add_f32_dpp v126, v126, v126 row_half_mirror row_mask:0xf bank_mask:0xf
	s_waitcnt lgkmcnt(0)
	s_nop 0
	s_nop 1
	v_add_f32_dpp v127, v127, v127 row_half_mirror row_mask:0xf bank_mask:0xf
	s_waitcnt lgkmcnt(0)
	s_nop 0
	s_nop 1
	v_add_f32_dpp v128, v128, v128 row_half_mirror row_mask:0xf bank_mask:0xf
	s_waitcnt lgkmcnt(0)
	s_nop 0
	s_nop 1
	v_add_f32_dpp v129, v129, v129 row_half_mirror row_mask:0xf bank_mask:0xf
	s_waitcnt lgkmcnt(0)
	s_nop 0
	s_nop 1
	v_add_f32_dpp v131, v131, v131 row_half_mirror row_mask:0xf bank_mask:0xf
	s_waitcnt lgkmcnt(0)
	s_nop 0
	s_nop 1
	v_add_f32_dpp v132, v132, v132 row_half_mirror row_mask:0xf bank_mask:0xf
	s_waitcnt lgkmcnt(0)
	s_nop 0
	s_nop 1
	v_add_f32_dpp v133, v133, v133 row_half_mirror row_mask:0xf bank_mask:0xf
	s_waitcnt lgkmcnt(0)
	s_nop 0
	s_nop 1
	v_add_f32_dpp v134, v134, v134 row_half_mirror row_mask:0xf bank_mask:0xf
	s_waitcnt lgkmcnt(0)
	s_nop 0
	s_nop 1
	v_add_f32_dpp v135, v135, v135 row_half_mirror row_mask:0xf bank_mask:0xf
	s_waitcnt lgkmcnt(0)
	s_nop 0
	s_nop 1
	v_add_f32_dpp v136, v136, v136 row_half_mirror row_mask:0xf bank_mask:0xf
	s_waitcnt lgkmcnt(0)
	s_nop 0
	s_nop 1
	v_add_f32_dpp v137, v137, v137 row_half_mirror row_mask:0xf bank_mask:0xf
	s_waitcnt lgkmcnt(0)
	s_nop 0
	s_nop 1
	v_add_f32_dpp v138, v138, v138 row_half_mirror row_mask:0xf bank_mask:0xf
	s_waitcnt lgkmcnt(0)
	s_nop 0
	s_nop 1
	v_add_f32_dpp v130, v130, v130 row_mirror row_mask:0xf bank_mask:0xf
	s_waitcnt lgkmcnt(0)
	s_nop 0
	s_nop 1
	v_add_f32_dpp v124, v124, v124 row_mirror row_mask:0xf bank_mask:0xf
	s_waitcnt lgkmcnt(0)
	s_nop 0
	s_nop 1
	v_add_f32_dpp v125, v125, v125 row_mirror row_mask:0xf bank_mask:0xf
	s_waitcnt lgkmcnt(0)
	s_nop 0
	s_nop 1
	v_add_f32_dpp v126, v126, v126 row_mirror row_mask:0xf bank_mask:0xf
	s_waitcnt lgkmcnt(0)
	s_nop 0
	s_nop 1
	v_add_f32_dpp v127, v127, v127 row_mirror row_mask:0xf bank_mask:0xf
	s_waitcnt lgkmcnt(0)
	s_nop 0
	s_nop 1
	v_add_f32_dpp v128, v128, v128 row_mirror row_mask:0xf bank_mask:0xf
	s_waitcnt lgkmcnt(0)
	s_nop 0
	s_nop 1
	v_add_f32_dpp v129, v129, v129 row_mirror row_mask:0xf bank_mask:0xf
	s_waitcnt lgkmcnt(0)
	s_nop 0
	s_nop 1
	v_add_f32_dpp v131, v131, v131 row_mirror row_mask:0xf bank_mask:0xf
	s_waitcnt lgkmcnt(0)
	s_nop 0
	s_nop 1
	v_add_f32_dpp v132, v132, v132 row_mirror row_mask:0xf bank_mask:0xf
	s_waitcnt lgkmcnt(0)
	s_nop 0
	s_nop 1
	v_add_f32_dpp v141, v133, v133 row_mirror row_mask:0xf bank_mask:0xf
	s_waitcnt lgkmcnt(0)
	s_nop 0
	s_nop 1
	v_add_f32_dpp v134, v134, v134 row_mirror row_mask:0xf bank_mask:0xf
	s_waitcnt lgkmcnt(0)
	s_nop 0
	s_nop 1
	v_add_f32_dpp v135, v135, v135 row_mirror row_mask:0xf bank_mask:0xf
	s_waitcnt lgkmcnt(0)
	s_nop 0
	s_nop 1
	v_add_f32_dpp v136, v136, v136 row_mirror row_mask:0xf bank_mask:0xf
	s_waitcnt lgkmcnt(0)
	s_nop 0
	s_nop 1
	v_add_f32_dpp v137, v137, v137 row_mirror row_mask:0xf bank_mask:0xf
	s_waitcnt lgkmcnt(0)
	s_nop 0
	s_nop 1
	v_add_f32_dpp v142, v138, v138 row_mirror row_mask:0xf bank_mask:0xf
	s_waitcnt lgkmcnt(0)
	s_nop 0
	v_mov_b32_e32 v133, v130
	s_nop 1
	v_permlane16_swap_b32_e32 v133, v130
	s_nop 1
	s_waitcnt lgkmcnt(0)
	v_add_f32_e32 v130, v130, v133
	ds_bpermute_b32 v133, v117, v124
	s_waitcnt lgkmcnt(0)
	v_add_f32_e32 v143, v124, v133
	ds_bpermute_b32 v124, v117, v125
	s_waitcnt lgkmcnt(0)
	v_add_f32_e32 v144, v125, v124
	ds_bpermute_b32 v125, v85, v130
	ds_bpermute_b32 v124, v117, v126
	ds_bpermute_b32 v149, v85, v144
	s_waitcnt lgkmcnt(2)
	v_add_f32_e32 v150, v130, v125
	v_fmamk_f32 v150, v150, 0x3b000000, v201
	v_cmp_gt_f32_e32 vcc, s91, v150
	v_mul_f32_e32 v152, 0x4f800000, v150
	s_waitcnt lgkmcnt(1)
	v_add_f32_e32 v145, v126, v124
	v_cndmask_b32_e32 v150, v150, v152, vcc
	v_sqrt_f32_e32 v152, v150
	ds_bpermute_b32 v124, v117, v127
	ds_bpermute_b32 v125, v85, v143
	ds_bpermute_b32 v147, v85, v145
	v_add_u32_e32 v153, -1, v152
	v_fma_f32 v154, -v153, v152, v150
	v_cmp_ge_f32_e64 s[46:47], 0, v154
	v_add_u32_e32 v154, 1, v152
	s_waitcnt lgkmcnt(2)
	v_add_f32_e32 v146, v127, v124
	v_cndmask_b32_e64 v153, v152, v153, s[46:47]
	v_fma_f32 v152, -v154, v152, v150
	v_cmp_lt_f32_e64 s[46:47], 0, v152
	ds_bpermute_b32 v124, v117, v128
	s_waitcnt lgkmcnt(2)
	v_add_f32_e32 v151, v143, v125
	v_cndmask_b32_e64 v152, v153, v154, s[46:47]
	v_mul_f32_e32 v153, 0x37800000, v152
	v_cndmask_b32_e32 v152, v152, v153, vcc
	v_cmp_class_f32_e32 vcc, v150, v202
	s_waitcnt lgkmcnt(0)
	v_add_f32_e32 v138, v128, v124
	ds_bpermute_b32 v124, v117, v129
	v_cndmask_b32_e32 v150, v152, v150, vcc
	v_div_scale_f32 v152, s[36:37], v150, v150, 1.0
	v_rcp_f32_e32 v153, v152
	s_waitcnt lgkmcnt(0)
	v_add_f32_e32 v139, v129, v124
	ds_bpermute_b32 v124, v117, v131
	v_fmamk_f32 v151, v151, 0x3b000000, v201
	v_fma_f32 v154, -v152, v153, 1.0
	v_fmac_f32_e32 v153, v154, v153
	v_div_scale_f32 v154, vcc, 1.0, v150, 1.0
	v_mul_f32_e32 v155, v154, v153
	v_fma_f32 v156, -v152, v155, v154
	v_fmac_f32_e32 v155, v156, v153
	v_fma_f32 v152, -v152, v155, v154
	v_div_fmas_f32 v152, v152, v153, v155
	s_waitcnt lgkmcnt(0)
	v_add_f32_e32 v140, v131, v124
	ds_bpermute_b32 v124, v117, v132
	v_div_fixup_f32 v150, v152, v150, 1.0
	v_cmp_gt_f32_e32 vcc, s91, v151
	v_mul_f32_e32 v152, 0x4f800000, v151
	ds_bpermute_b32 v148, v85, v146
	v_cndmask_b32_e32 v151, v151, v152, vcc
	v_sqrt_f32_e32 v152, v151
	s_waitcnt lgkmcnt(1)
	v_add_f32_e32 v133, v132, v124
	ds_bpermute_b32 v124, v117, v141
	ds_bpermute_b32 v143, v85, v138
	v_add_u32_e32 v153, -1, v152
	v_fma_f32 v154, -v153, v152, v151
	v_cmp_ge_f32_e64 s[46:47], 0, v154
	v_add_u32_e32 v154, 1, v152
	s_waitcnt lgkmcnt(1)
	v_add_f32_e32 v132, v141, v124
	v_cndmask_b32_e64 v153, v152, v153, s[46:47]
	v_fma_f32 v152, -v154, v152, v151
	ds_bpermute_b32 v124, v117, v134
	v_cmp_lt_f32_e64 s[46:47], 0, v152
	ds_bpermute_b32 v141, v85, v139
	s_waitcnt lgkmcnt(1)
	v_add_f32_e32 v134, v134, v124
	v_cndmask_b32_e64 v152, v153, v154, s[46:47]
	v_mul_f32_e32 v153, 0x37800000, v152
	v_cndmask_b32_e32 v152, v152, v153, vcc
	v_cmp_class_f32_e32 vcc, v151, v202
	ds_bpermute_b32 v124, v117, v135
	s_waitcnt lgkmcnt(0)
	v_add_f32_e32 v128, v135, v124
	v_cndmask_b32_e32 v151, v152, v151, vcc
	v_div_scale_f32 v152, s[36:37], v151, v151, 1.0
	v_rcp_f32_e32 v153, v152
	ds_bpermute_b32 v124, v117, v136
	v_pk_mul_f32 v[80:81], v[80:81], v[150:151] op_sel_hi:[1,0]
	v_pk_mul_f32 v[82:83], v[82:83], v[150:151] op_sel_hi:[1,0]
	v_fma_f32 v154, -v152, v153, 1.0
	v_fmac_f32_e32 v153, v154, v153
	v_div_scale_f32 v154, vcc, 1.0, v151, 1.0
	v_mul_f32_e32 v155, v154, v153
	v_fma_f32 v156, -v152, v155, v154
	v_fmac_f32_e32 v155, v156, v153
	s_waitcnt lgkmcnt(0)
	v_add_f32_e32 v126, v136, v124
	ds_bpermute_b32 v124, v117, v137
	v_fma_f32 v152, -v152, v155, v154
	v_div_fmas_f32 v152, v152, v153, v155
	v_lshl_add_u64 v[154:155], s[58:59], 0, v[100:101]
	v_div_fixup_f32 v152, v152, v151, 1.0
	v_cvt_pk_bf16_f32 v80, v80, v81
	v_cvt_pk_bf16_f32 v81, v82, v83
	v_add_co_u32_e32 v82, vcc, s33, v154
	v_pk_mul_f32 v[76:77], v[76:77], v[152:153] op_sel_hi:[1,0]
	s_nop 0
	v_addc_co_u32_e32 v83, vcc, 0, v155, vcc
	v_pk_mul_f32 v[78:79], v[78:79], v[152:153] op_sel_hi:[1,0]
	s_mov_b32 s33, 0x56f80000
	v_cvt_pk_bf16_f32 v76, v76, v77
	v_cvt_pk_bf16_f32 v77, v78, v79
	v_add_co_u32_e32 v78, vcc, s33, v154
	v_pk_mul_f32 v[68:69], v[68:69], v[152:153] op_sel_hi:[1,0]
	v_pk_mul_f32 v[70:71], v[70:71], v[152:153] op_sel_hi:[1,0]
	s_waitcnt lgkmcnt(0)
	v_add_f32_e32 v127, v137, v124
	ds_bpermute_b32 v124, v117, v142
	v_addc_co_u32_e32 v79, vcc, 0, v155, vcc
	v_cvt_pk_bf16_f32 v68, v68, v69
	v_cvt_pk_bf16_f32 v69, v70, v71
	global_store_dwordx2 v[78:79], v[68:69], off offset:512
	v_mul_f32_e32 v68, v118, v123
	ds_bpermute_b32 v69, v85, v68
	s_waitcnt lgkmcnt(1)
	v_add_f32_e32 v124, v142, v124
	ds_bpermute_b32 v142, v85, v140
	ds_bpermute_b32 v137, v85, v133
	ds_bpermute_b32 v135, v85, v132
	ds_bpermute_b32 v136, v85, v134
	ds_bpermute_b32 v131, v85, v128
	ds_bpermute_b32 v129, v85, v126
	ds_bpermute_b32 v130, v85, v127
	ds_bpermute_b32 v125, v85, v124
	s_waitcnt lgkmcnt(8)
	v_mul_f32_e32 v69, v113, v69
	v_cndmask_b32_e64 v69, v69, -v69, s[42:43]
	v_pk_mul_f32 v[72:73], v[72:73], v[150:151] op_sel_hi:[1,0]
	v_pk_mul_f32 v[74:75], v[74:75], v[150:151] op_sel_hi:[1,0]
	v_fmac_f32_e32 v69, v68, v112
	v_cvt_pk_bf16_f32 v72, v72, v73
	v_cvt_pk_bf16_f32 v73, v74, v75
	v_cvt_pk_bf16_f32 v70, v69, s0
	v_lshl_add_u64 v[68:69], s[58:59], 0, v[98:99]
	global_store_dwordx2 v[82:83], v[80:81], off
	global_store_dwordx2 v[78:79], v[76:77], off
	global_store_dwordx2 v[82:83], v[72:73], off offset:512
	global_store_short v[68:69], v70, off
	s_and_saveexec_b64 s[36:37], s[44:45]
	s_cbranch_execz .LBB0_576
	s_add_u32 s38, s58, s11
	s_addc_u32 s39, s59, s15
	v_add_f32_e32 v68, v144, v149
	global_store_dword v3, v68, s[38:39]

.LBB0_582:
	s_or_b64 exec, exec, s[30:31]
	v_add_f32_e32 v20, v126, v129
	v_fmamk_f32 v20, v20, 0x3b000000, v201
	v_cmp_gt_f32_e32 vcc, s91, v20
	v_mul_f32_e32 v22, 0x4f800000, v20
	v_add_f32_e32 v21, v127, v130
	v_cndmask_b32_e32 v20, v20, v22, vcc
	v_sqrt_f32_e32 v22, v20
	v_fmamk_f32 v21, v21, 0x3b000000, v201
	v_add_u32_e32 v23, -1, v22
	v_fma_f32 v24, -v23, v22, v20
	v_cmp_ge_f32_e64 s[46:47], 0, v24
	v_add_u32_e32 v24, 1, v22
	s_nop 0
	v_cndmask_b32_e64 v23, v22, v23, s[46:47]
	v_fma_f32 v22, -v24, v22, v20
	v_cmp_lt_f32_e64 s[46:47], 0, v22
	s_nop 1
	v_cndmask_b32_e64 v22, v23, v24, s[46:47]
	v_mul_f32_e32 v23, 0x37800000, v22
	v_cndmask_b32_e32 v22, v22, v23, vcc
	v_cmp_class_f32_e32 vcc, v20, v202
	s_nop 1
	v_cndmask_b32_e32 v20, v22, v20, vcc
	v_div_scale_f32 v22, s[28:29], v20, v20, 1.0
	v_rcp_f32_e32 v23, v22
	s_nop 0
	v_fma_f32 v24, -v22, v23, 1.0
	v_fmac_f32_e32 v23, v24, v23
	v_div_scale_f32 v24, vcc, 1.0, v20, 1.0
	v_mul_f32_e32 v25, v24, v23
	v_fma_f32 v26, -v22, v25, v24
	v_fmac_f32_e32 v25, v26, v23
	v_fma_f32 v22, -v22, v25, v24
	v_div_fmas_f32 v22, v22, v23, v25
	v_div_fixup_f32 v20, v22, v20, 1.0
	v_cmp_gt_f32_e32 vcc, s91, v21
	v_mul_f32_e32 v22, 0x4f800000, v21
	s_nop 0
	v_cndmask_b32_e32 v21, v21, v22, vcc
	v_sqrt_f32_e32 v22, v21
	s_nop 0
	v_add_u32_e32 v23, -1, v22
	v_fma_f32 v24, -v23, v22, v21
	v_cmp_ge_f32_e64 s[46:47], 0, v24
	v_add_u32_e32 v24, 1, v22
	s_nop 0
	v_cndmask_b32_e64 v23, v22, v23, s[46:47]
	v_fma_f32 v22, -v24, v22, v21
	v_cmp_lt_f32_e64 s[46:47], 0, v22
	s_nop 1
	v_cndmask_b32_e64 v22, v23, v24, s[46:47]
	v_mul_f32_e32 v23, 0x37800000, v22
	v_cndmask_b32_e32 v22, v22, v23, vcc
	v_cmp_class_f32_e32 vcc, v21, v202
	s_nop 1
	v_cndmask_b32_e32 v21, v22, v21, vcc
	v_div_scale_f32 v22, s[28:29], v21, v21, 1.0
	v_rcp_f32_e32 v23, v22
	s_lshl_b64 s[28:29], s[26:27], 10
	v_pk_mul_f32 v[16:17], v[16:17], v[20:21] op_sel_hi:[1,0]
	v_pk_mul_f32 v[18:19], v[18:19], v[20:21] op_sel_hi:[1,0]
	v_fma_f32 v24, -v22, v23, 1.0
	v_fmac_f32_e32 v23, v24, v23
	v_div_scale_f32 v24, vcc, 1.0, v21, 1.0
	v_mul_f32_e32 v25, v24, v23
	v_fma_f32 v26, -v22, v25, v24
	v_fmac_f32_e32 v25, v26, v23
	v_fma_f32 v22, -v22, v25, v24
	v_div_fmas_f32 v22, v22, v23, v25
	v_div_fixup_f32 v22, v22, v21, 1.0
	v_pk_mul_f32 v[4:5], v[4:5], v[22:23] op_sel_hi:[1,0]
	v_pk_mul_f32 v[6:7], v[6:7], v[22:23] op_sel_hi:[1,0]
	v_lshl_add_u64 v[26:27], v[94:95], 0, s[28:29]
	v_cvt_pk_bf16_f32 v4, v4, v5
	v_cvt_pk_bf16_f32 v5, v6, v7
	global_store_dwordx2 v[26:27], v[4:5], off offset:512
	v_mul_f32_e32 v4, v118, v119
	ds_bpermute_b32 v5, v85, v4
	v_lshl_add_u64 v[24:25], v[92:93], 0, s[28:29]
	v_pk_mul_f32 v[12:13], v[12:13], v[22:23] op_sel_hi:[1,0]
	v_pk_mul_f32 v[14:15], v[14:15], v[22:23] op_sel_hi:[1,0]
	v_pk_mul_f32 v[8:9], v[8:9], v[20:21] op_sel_hi:[1,0]
	s_waitcnt vmcnt(21) lgkmcnt(0)
	v_mul_f32_e32 v5, v105, v5
	v_cndmask_b32_e64 v5, v5, -v5, s[42:43]
	v_pk_mul_f32 v[10:11], v[10:11], v[20:21] op_sel_hi:[1,0]
	v_fmac_f32_e32 v5, v4, v104
	s_lshl_b64 s[28:29], s[26:27], 7
	v_cvt_pk_bf16_f32 v16, v16, v17
	v_cvt_pk_bf16_f32 v17, v18, v19
	v_cvt_pk_bf16_f32 v12, v12, v13
	v_cvt_pk_bf16_f32 v13, v14, v15
	v_cvt_pk_bf16_f32 v8, v8, v9
	v_cvt_pk_bf16_f32 v9, v10, v11
	v_cvt_pk_bf16_f32 v6, v5, s0
	v_lshl_add_u64 v[4:5], v[96:97], 0, s[28:29]
	global_store_dwordx2 v[24:25], v[16:17], off
	global_store_dwordx2 v[26:27], v[12:13], off
	global_store_dwordx2 v[24:25], v[8:9], off offset:512
	global_store_short v[4:5], v6, off
	s_and_saveexec_b64 s[28:29], s[44:45]
	s_cbranch_execz .LBB0_545
	s_lshl_b64 s[26:27], s[26:27], 2
	s_add_u32 s26, s8, s26
	v_add_f32_e32 v4, v124, v125
	s_addc_u32 s27, s9, s27
	global_store_dword v3, v4, s[26:27]
	s_branch .LBB0_545
	s_nop 0
	s_nop 0
	s_nop 0
	s_nop 0
	s_nop 0
	s_nop 0
	s_nop 0
	s_nop 0
	s_nop 0
	s_nop 0
	s_nop 0
	s_nop 0
	s_nop 0
	s_nop 0

.LBB0_771:
	v_and_b32_e32 v9, 0xffff0000, v39
	v_and_b32_e32 v8, 0xffff0000, v38
	v_lshlrev_b32_e32 v7, 16, v39
	v_lshlrev_b32_e32 v6, 16, v38
	v_pk_mul_f32 v[10:11], v[8:9], v[8:9]
	v_lshl_add_u64 v[4:5], v[26:27], 0, s[18:19]
	v_pk_fma_f32 v[10:11], v[6:7], v[6:7], v[10:11]
	s_add_u32 s18, s12, s18
	v_add_f32_e32 v10, v10, v11
	s_nop 1
	v_add_f32_dpp v10, v10, v10 quad_perm:[1,0,3,2] row_mask:0xf bank_mask:0xf
	s_addc_u32 s19, s13, s19
	s_mov_b32 s3, 0x7b9ea000
	s_add_i32 s16, s16, s1
	s_cmpk_gt_i32 s16, 0x27ff
	s_waitcnt lgkmcnt(0)
	s_nop 0
	s_nop 1
	v_add_f32_dpp v10, v10, v10 quad_perm:[2,3,0,1] row_mask:0xf bank_mask:0xf
	s_waitcnt lgkmcnt(0)
	s_nop 0
	s_nop 1
	v_add_f32_dpp v10, v10, v10 row_half_mirror row_mask:0xf bank_mask:0xf
	s_waitcnt lgkmcnt(0)
	s_nop 0
	s_nop 1
	v_add_f32_dpp v10, v10, v10 row_mirror row_mask:0xf bank_mask:0xf
	s_waitcnt lgkmcnt(0)
	s_nop 0
	v_mov_b32_e32 v11, v10
	s_nop 1
	v_permlane16_swap_b32_e32 v11, v10
	s_nop 1
	s_waitcnt lgkmcnt(0)
	v_add_f32_e32 v10, v10, v11
	v_mov_b32_e32 v11, v10
	s_nop 1
	v_permlane32_swap_b32_e32 v11, v10
	s_nop 1
	s_waitcnt lgkmcnt(0)
	v_add_f32_e32 v10, v10, v11
	v_fmamk_f32 v10, v10, 0x3b800000, v201
	v_cmp_gt_f32_e32 vcc, s91, v10
	v_mul_f32_e32 v11, 0x4f800000, v10
	s_nop 0
	v_cndmask_b32_e32 v10, v10, v11, vcc
	v_sqrt_f32_e32 v11, v10
	s_nop 0
	v_add_u32_e32 v38, -1, v11
	v_fma_f32 v39, -v38, v11, v10
	v_cmp_ge_f32_e64 s[46:47], 0, v39
	v_add_u32_e32 v39, 1, v11
	s_nop 0
	v_cndmask_b32_e64 v38, v11, v38, s[46:47]
	v_fma_f32 v11, -v39, v11, v10
	v_cmp_lt_f32_e64 s[46:47], 0, v11
	s_nop 1
	v_cndmask_b32_e64 v11, v38, v39, s[46:47]
	v_mul_f32_e32 v38, 0x37800000, v11
	v_cndmask_b32_e32 v11, v11, v38, vcc
	v_cmp_class_f32_e32 vcc, v10, v202
	s_nop 1
	v_cndmask_b32_e32 v10, v11, v10, vcc
	v_div_scale_f32 v11, s[4:5], v10, v10, 1.0
	v_rcp_f32_e32 v38, v11
	s_nop 0
	v_fma_f32 v39, -v11, v38, 1.0
	v_fmac_f32_e32 v38, v39, v38
	v_div_scale_f32 v39, vcc, 1.0, v10, 1.0
	v_mul_f32_e32 v40, v39, v38
	v_fma_f32 v41, -v11, v40, v39
	v_fmac_f32_e32 v40, v41, v38
	v_fma_f32 v11, -v11, v40, v39
	v_div_fmas_f32 v11, v11, v38, v40
	v_div_fixup_f32 v10, v11, v10, 1.0
	v_mov_b32_e32 v38, v6
	v_mov_b32_e32 v39, v8
	v_mov_b32_e32 v8, v7
	v_pk_mul_f32 v[38:39], v[10:11], v[38:39] op_sel_hi:[0,1]
	v_pk_mul_f32 v[6:7], v[10:11], v[8:9] op_sel_hi:[0,1]
	v_pk_mul_f32 v[6:7], v[28:29], v[6:7]
	v_pk_mul_f32 v[8:9], v[30:31], v[38:39]
	s_nop 0
	v_cvt_pk_bf16_f32 v8, v8, v9
	v_cvt_pk_bf16_f32 v9, v6, v7
	v_and_b32_e32 v7, 0xffff0000, v37
	v_and_b32_e32 v6, 0xffff0000, v36
	global_store_dwordx2 v[4:5], v[8:9], off
	v_lshlrev_b32_e32 v5, 16, v37
	v_lshlrev_b32_e32 v4, 16, v36
	v_pk_mul_f32 v[8:9], v[6:7], v[6:7]
	s_nop 0
	v_pk_fma_f32 v[8:9], v[4:5], v[4:5], v[8:9]
	s_nop 0
	v_add_f32_e32 v8, v8, v9
	s_nop 1
	v_add_f32_dpp v8, v8, v8 quad_perm:[1,0,3,2] row_mask:0xf bank_mask:0xf
	s_waitcnt lgkmcnt(0)
	s_nop 0
	s_nop 1
	v_add_f32_dpp v8, v8, v8 quad_perm:[2,3,0,1] row_mask:0xf bank_mask:0xf
	s_waitcnt lgkmcnt(0)
	s_nop 0
	s_nop 1
	v_add_f32_dpp v8, v8, v8 row_half_mirror row_mask:0xf bank_mask:0xf
	s_waitcnt lgkmcnt(0)
	s_nop 0
	s_nop 1
	v_add_f32_dpp v8, v8, v8 row_mirror row_mask:0xf bank_mask:0xf
	s_waitcnt lgkmcnt(0)
	s_nop 0
	v_mov_b32_e32 v9, v8
	s_nop 1
	v_permlane16_swap_b32_e32 v9, v8
	s_nop 1
	s_waitcnt lgkmcnt(0)
	v_add_f32_e32 v8, v8, v9
	v_mov_b32_e32 v9, v8
	s_nop 1
	v_permlane32_swap_b32_e32 v9, v8
	s_nop 1
	s_waitcnt lgkmcnt(0)
	v_add_f32_e32 v8, v8, v9
	v_fmamk_f32 v8, v8, 0x3b800000, v201
	v_cmp_gt_f32_e32 vcc, s91, v8
	v_mul_f32_e32 v9, 0x4f800000, v8
	s_nop 0
	v_cndmask_b32_e32 v8, v8, v9, vcc
	v_sqrt_f32_e32 v9, v8
	s_nop 0
	v_add_u32_e32 v10, -1, v9
	v_fma_f32 v11, -v10, v9, v8
	v_cmp_ge_f32_e64 s[46:47], 0, v11
	v_add_u32_e32 v11, 1, v9
	s_nop 0
	v_cndmask_b32_e64 v10, v9, v10, s[46:47]
	v_fma_f32 v9, -v11, v9, v8
	v_cmp_lt_f32_e64 s[46:47], 0, v9
	s_nop 1
	v_cndmask_b32_e64 v9, v10, v11, s[46:47]
	v_mul_f32_e32 v10, 0x37800000, v9
	v_cndmask_b32_e32 v9, v9, v10, vcc
	v_cmp_class_f32_e32 vcc, v8, v202
	s_nop 1
	v_cndmask_b32_e32 v8, v9, v8, vcc
	v_div_scale_f32 v9, s[4:5], v8, v8, 1.0
	v_rcp_f32_e32 v10, v9
	s_nop 0
	v_fma_f32 v11, -v9, v10, 1.0
	v_fmac_f32_e32 v10, v11, v10
	v_div_scale_f32 v11, vcc, 1.0, v8, 1.0
	v_mul_f32_e32 v36, v11, v10
	v_fma_f32 v37, -v9, v36, v11
	v_fmac_f32_e32 v36, v37, v10
	v_fma_f32 v9, -v9, v36, v11
	v_div_fmas_f32 v9, v9, v10, v36
	v_div_fixup_f32 v8, v9, v8, 1.0
	v_mov_b32_e32 v10, v4
	v_mov_b32_e32 v11, v6
	v_mov_b32_e32 v6, v5
	v_pk_mul_f32 v[10:11], v[8:9], v[10:11] op_sel_hi:[0,1]
	v_pk_mul_f32 v[4:5], v[8:9], v[6:7] op_sel_hi:[0,1]
	v_pk_mul_f32 v[4:5], v[28:29], v[4:5]
	v_pk_mul_f32 v[6:7], v[30:31], v[10:11]
	v_and_b32_e32 v9, 0xffff0000, v35
	v_cvt_pk_bf16_f32 v6, v6, v7
	v_cvt_pk_bf16_f32 v7, v4, v5
	v_lshl_add_u64 v[4:5], s[18:19], 0, v[2:3]
	v_add_co_u32_e32 v4, vcc, s3, v4
	v_and_b32_e32 v8, 0xffff0000, v34
	s_nop 0
	v_addc_co_u32_e32 v5, vcc, 0, v5, vcc
	global_store_dwordx2 v[4:5], v[6:7], off offset:512
	v_lshlrev_b32_e32 v7, 16, v35
	v_lshlrev_b32_e32 v6, 16, v34
	v_pk_mul_f32 v[10:11], v[8:9], v[8:9]
	s_nop 0
	v_pk_fma_f32 v[10:11], v[6:7], v[6:7], v[10:11]
	s_nop 0
	v_add_f32_e32 v10, v10, v11
	s_nop 1
	v_add_f32_dpp v10, v10, v10 quad_perm:[1,0,3,2] row_mask:0xf bank_mask:0xf
	s_waitcnt lgkmcnt(0)
	s_nop 0
	s_nop 1
	v_add_f32_dpp v10, v10, v10 quad_perm:[2,3,0,1] row_mask:0xf bank_mask:0xf
	s_waitcnt lgkmcnt(0)
	s_nop 0
	s_nop 1
	v_add_f32_dpp v10, v10, v10 row_half_mirror row_mask:0xf bank_mask:0xf
	s_waitcnt lgkmcnt(0)
	s_nop 0
	s_nop 1
	v_add_f32_dpp v10, v10, v10 row_mirror row_mask:0xf bank_mask:0xf
	s_waitcnt lgkmcnt(0)
	s_nop 0
	v_mov_b32_e32 v11, v10
	s_nop 1
	v_permlane16_swap_b32_e32 v11, v10
	s_nop 1
	s_waitcnt lgkmcnt(0)
	v_add_f32_e32 v10, v10, v11
	v_mov_b32_e32 v11, v10
	s_nop 1
	v_permlane32_swap_b32_e32 v11, v10
	s_nop 1
	s_waitcnt lgkmcnt(0)
	v_add_f32_e32 v10, v10, v11
	v_fmamk_f32 v10, v10, 0x3b800000, v201
	v_cmp_gt_f32_e32 vcc, s91, v10
	v_mul_f32_e32 v11, 0x4f800000, v10
	s_nop 0
	v_cndmask_b32_e32 v10, v10, v11, vcc
	v_sqrt_f32_e32 v11, v10
	s_nop 0
	v_add_u32_e32 v34, -1, v11
	v_fma_f32 v35, -v34, v11, v10
	v_cmp_ge_f32_e64 s[46:47], 0, v35
	v_add_u32_e32 v35, 1, v11
	s_nop 0
	v_cndmask_b32_e64 v34, v11, v34, s[46:47]
	v_fma_f32 v11, -v35, v11, v10
	v_cmp_lt_f32_e64 s[46:47], 0, v11
	s_nop 1
	v_cndmask_b32_e64 v11, v34, v35, s[46:47]
	v_mul_f32_e32 v34, 0x37800000, v11
	v_cndmask_b32_e32 v11, v11, v34, vcc
	v_cmp_class_f32_e32 vcc, v10, v202
	s_nop 1
	v_cndmask_b32_e32 v10, v11, v10, vcc
	v_div_scale_f32 v11, s[4:5], v10, v10, 1.0
	v_rcp_f32_e32 v34, v11
	s_nop 0
	v_fma_f32 v35, -v11, v34, 1.0
	v_fmac_f32_e32 v34, v35, v34
	v_div_scale_f32 v35, vcc, 1.0, v10, 1.0
	v_mul_f32_e32 v36, v35, v34
	v_fma_f32 v37, -v11, v36, v35
	v_fmac_f32_e32 v36, v37, v34
	v_fma_f32 v11, -v11, v36, v35
	v_div_fmas_f32 v11, v11, v34, v36
	v_div_fixup_f32 v10, v11, v10, 1.0
	v_mov_b32_e32 v34, v6
	v_mov_b32_e32 v35, v8
	v_mov_b32_e32 v8, v7
	v_pk_mul_f32 v[34:35], v[10:11], v[34:35] op_sel_hi:[0,1]
	v_pk_mul_f32 v[6:7], v[10:11], v[8:9] op_sel_hi:[0,1]
	v_pk_mul_f32 v[6:7], v[28:29], v[6:7]
	v_pk_mul_f32 v[8:9], v[30:31], v[34:35]
	s_nop 0
	v_cvt_pk_bf16_f32 v8, v8, v9
	v_cvt_pk_bf16_f32 v9, v6, v7
	global_store_dwordx2 v[4:5], v[8:9], off offset:1024
	v_and_b32_e32 v9, 0xffff0000, v33
	v_and_b32_e32 v8, 0xffff0000, v32
	v_lshlrev_b32_e32 v7, 16, v33
	v_lshlrev_b32_e32 v6, 16, v32
	v_pk_mul_f32 v[10:11], v[8:9], v[8:9]
	s_nop 0
	v_pk_fma_f32 v[10:11], v[6:7], v[6:7], v[10:11]
	s_nop 0
	v_add_f32_e32 v10, v10, v11
	s_nop 1
	v_add_f32_dpp v10, v10, v10 quad_perm:[1,0,3,2] row_mask:0xf bank_mask:0xf
	s_waitcnt lgkmcnt(0)
	s_nop 0
	s_nop 1
	v_add_f32_dpp v10, v10, v10 quad_perm:[2,3,0,1] row_mask:0xf bank_mask:0xf
	s_waitcnt lgkmcnt(0)
	s_nop 0
	s_nop 1
	v_add_f32_dpp v10, v10, v10 row_half_mirror row_mask:0xf bank_mask:0xf
	s_waitcnt lgkmcnt(0)
	s_nop 0
	s_nop 1
	v_add_f32_dpp v10, v10, v10 row_mirror row_mask:0xf bank_mask:0xf
	s_waitcnt lgkmcnt(0)
	s_nop 0
	v_mov_b32_e32 v11, v10
	s_nop 1
	v_permlane16_swap_b32_e32 v11, v10
	s_nop 1
	s_waitcnt lgkmcnt(0)
	v_add_f32_e32 v10, v10, v11
	v_mov_b32_e32 v11, v10
	s_nop 1
	v_permlane32_swap_b32_e32 v11, v10
	s_nop 1
	s_waitcnt lgkmcnt(0)
	v_add_f32_e32 v10, v10, v11
	v_fmamk_f32 v10, v10, 0x3b800000, v201
	v_cmp_gt_f32_e32 vcc, s91, v10
	v_mul_f32_e32 v11, 0x4f800000, v10
	s_nop 0
	v_cndmask_b32_e32 v10, v10, v11, vcc
	v_sqrt_f32_e32 v11, v10
	s_nop 0
	v_add_u32_e32 v32, -1, v11
	v_fma_f32 v33, -v32, v11, v10
	v_cmp_ge_f32_e64 s[46:47], 0, v33
	v_add_u32_e32 v33, 1, v11
	s_nop 0
	v_cndmask_b32_e64 v32, v11, v32, s[46:47]
	v_fma_f32 v11, -v33, v11, v10
	v_cmp_lt_f32_e64 s[46:47], 0, v11
	s_nop 1
	v_cndmask_b32_e64 v11, v32, v33, s[46:47]
	v_mul_f32_e32 v32, 0x37800000, v11
	v_cndmask_b32_e32 v11, v11, v32, vcc
	v_cmp_class_f32_e32 vcc, v10, v202
	s_nop 1
	v_cndmask_b32_e32 v10, v11, v10, vcc
	v_div_scale_f32 v11, s[4:5], v10, v10, 1.0
	v_rcp_f32_e32 v32, v11
	s_nop 0
	v_fma_f32 v33, -v11, v32, 1.0
	v_fmac_f32_e32 v32, v33, v32
	v_div_scale_f32 v33, vcc, 1.0, v10, 1.0
	v_mul_f32_e32 v34, v33, v32
	v_fma_f32 v35, -v11, v34, v33
	v_fmac_f32_e32 v34, v35, v32
	v_fma_f32 v11, -v11, v34, v33
	v_div_fmas_f32 v11, v11, v32, v34
	v_div_fixup_f32 v10, v11, v10, 1.0
	v_mov_b32_e32 v32, v6
	v_mov_b32_e32 v33, v8
	v_mov_b32_e32 v8, v7
	v_pk_mul_f32 v[32:33], v[10:11], v[32:33] op_sel_hi:[0,1]
	v_pk_mul_f32 v[6:7], v[10:11], v[8:9] op_sel_hi:[0,1]
	v_pk_mul_f32 v[6:7], v[28:29], v[6:7]
	v_pk_mul_f32 v[8:9], v[30:31], v[32:33]
	s_nop 0
	v_cvt_pk_bf16_f32 v8, v8, v9
	v_cvt_pk_bf16_f32 v9, v6, v7
	global_store_dwordx2 v[4:5], v[8:9], off offset:1536
	s_cbranch_scc1 .LBB0_822
